# v24 with DFT twiddle generation moved under the staging-load latency
# speedup vs baseline: 1.0152x; 1.0152x over previous
; __device__ __forceinline__ void phase_prep(const Params& P, int l, unsigned char* lds) {
;     ...
;             const int n0 = (tid & 63) * 4, t8 = (tid >> 6) * 8, cp0 = n0 & 63, g = n0 >> 6;
;             const bool sp0 = (!is_ctx) && (t0 == CTX) && (t8 == 0);
;             float aC[4][8], aS[4][8];
; #pragma unroll
;             for (int q = 0; q < 4; ++q)
; #pragma unroll
;                 for (int t = 0; t < 8; ++t) { aC[q][t] = 0.f; aS[q][t] = 0.f; }
;             const float* ub = U + t8 * 256 + g * 64;
;             const float* ub2 = is_ctx ? ub : ub + 64 * 256;
; #pragma unroll 2
;             for (int c = 0; c < 64; ++c) {
;                 float cv[4], sv[4];
; #pragma unroll
;                 for (int q = 0; q < 4; ++q) { const float rev = (float)((c * (cp0 + q)) & 63) * (1.0f / 64.0f); cv[q] = __builtin_amdgcn_cosf(rev) * 0.125f; sv[q] = __builtin_amdgcn_sinf(rev) * 0.125f; }
; #pragma unroll
;                 for (int t = 0; t < 8; ++t) { const float u = ub[t * 256 + c], u2 = ub2[t * 256 + c];
; #pragma unroll
;                     for (int q = 0; q < 4; ++q) { aC[q][t] += u * cv[q]; aS[q][t] += u2 * ((t == 0 && sp0) ? cv[q] : sv[q]); } }
.Ldft_st_ctx:
	s_lshl_b32 s7, s12, 13
	v_lshl_add_u32 v35, v32, 2, s7
	v_add_u32_e32 v36, 0x10000, v35
	v_add_u32_e32 v41, 32, v34
	v_mul_u32_u24_e32 v120, v33, v34
	v_mul_u32_u24_e32 v121, v33, v41
	v_lshlrev_b32_e32 v122, 1, v34
	v_lshlrev_b32_e32 v123, 1, v41
	v_and_b32_e32 v41, 63, v120
	v_cvt_f32_u32_e32 v41, v41
	v_mul_f32_e32 v41, 0x3c800000, v41
	v_cos_f32_e32 v42, v41
	v_sin_f32_e32 v43, v41
	v_add_u32_e32 v120, v120, v122
	v_mul_f32_e32 v130, 0x3e000000, v42
	v_mul_f32_e32 v194, 0x3e000000, v43
	v_and_b32_e32 v41, 63, v121
	v_cvt_f32_u32_e32 v41, v41
	v_mul_f32_e32 v41, 0x3c800000, v41
	v_cos_f32_e32 v42, v41
	v_sin_f32_e32 v43, v41
	v_add_u32_e32 v121, v121, v123
	v_mul_f32_e32 v162, 0x3e000000, v42
	v_mul_f32_e32 v230, 0x3e000000, v43
	v_and_b32_e32 v41, 63, v120
	v_cvt_f32_u32_e32 v41, v41
	v_mul_f32_e32 v41, 0x3c800000, v41
	v_cos_f32_e32 v42, v41
	v_sin_f32_e32 v43, v41
	v_add_u32_e32 v120, v120, v122
	v_mul_f32_e32 v131, 0x3e000000, v42
	v_mul_f32_e32 v195, 0x3e000000, v43
	v_and_b32_e32 v41, 63, v121
	v_cvt_f32_u32_e32 v41, v41
	v_mul_f32_e32 v41, 0x3c800000, v41
	v_cos_f32_e32 v42, v41
	v_sin_f32_e32 v43, v41
	v_add_u32_e32 v121, v121, v123
	v_mul_f32_e32 v163, 0x3e000000, v42
	v_mul_f32_e32 v231, 0x3e000000, v43
	v_and_b32_e32 v41, 63, v120
	v_cvt_f32_u32_e32 v41, v41
	v_mul_f32_e32 v41, 0x3c800000, v41
	v_cos_f32_e32 v42, v41
	v_sin_f32_e32 v43, v41
	v_add_u32_e32 v120, v120, v122
	v_mul_f32_e32 v132, 0x3e000000, v42
	v_mul_f32_e32 v196, 0x3e000000, v43
	v_and_b32_e32 v41, 63, v121
	v_cvt_f32_u32_e32 v41, v41
	v_mul_f32_e32 v41, 0x3c800000, v41
	v_cos_f32_e32 v42, v41
	v_sin_f32_e32 v43, v41
	v_add_u32_e32 v121, v121, v123
	v_mul_f32_e32 v164, 0x3e000000, v42
	v_mul_f32_e32 v232, 0x3e000000, v43
	v_and_b32_e32 v41, 63, v120
	v_cvt_f32_u32_e32 v41, v41
	v_mul_f32_e32 v41, 0x3c800000, v41
	v_cos_f32_e32 v42, v41
	v_sin_f32_e32 v43, v41
	v_add_u32_e32 v120, v120, v122
	v_mul_f32_e32 v133, 0x3e000000, v42
	v_mul_f32_e32 v197, 0x3e000000, v43
	v_and_b32_e32 v41, 63, v121
	v_cvt_f32_u32_e32 v41, v41
	v_mul_f32_e32 v41, 0x3c800000, v41
	v_cos_f32_e32 v42, v41
	v_sin_f32_e32 v43, v41
	v_add_u32_e32 v121, v121, v123
	v_mul_f32_e32 v165, 0x3e000000, v42
	v_mul_f32_e32 v233, 0x3e000000, v43
	v_and_b32_e32 v41, 63, v120
	v_cvt_f32_u32_e32 v41, v41
	v_mul_f32_e32 v41, 0x3c800000, v41
	v_cos_f32_e32 v42, v41
	v_sin_f32_e32 v43, v41
	v_add_u32_e32 v120, v120, v122
	v_mul_f32_e32 v134, 0x3e000000, v42
	v_mul_f32_e32 v198, 0x3e000000, v43
	v_and_b32_e32 v41, 63, v121
	v_cvt_f32_u32_e32 v41, v41
	v_mul_f32_e32 v41, 0x3c800000, v41
	v_cos_f32_e32 v42, v41
	v_sin_f32_e32 v43, v41
	v_add_u32_e32 v121, v121, v123
	v_mul_f32_e32 v166, 0x3e000000, v42
	v_mul_f32_e32 v234, 0x3e000000, v43
	v_and_b32_e32 v41, 63, v120
	v_cvt_f32_u32_e32 v41, v41
	v_mul_f32_e32 v41, 0x3c800000, v41
	v_cos_f32_e32 v42, v41
	v_sin_f32_e32 v43, v41
	v_add_u32_e32 v120, v120, v122
	v_mul_f32_e32 v135, 0x3e000000, v42
	v_mul_f32_e32 v199, 0x3e000000, v43
	v_and_b32_e32 v41, 63, v121
	v_cvt_f32_u32_e32 v41, v41
	v_mul_f32_e32 v41, 0x3c800000, v41
	v_cos_f32_e32 v42, v41
	v_sin_f32_e32 v43, v41
	v_add_u32_e32 v121, v121, v123
	v_mul_f32_e32 v167, 0x3e000000, v42
	v_mul_f32_e32 v235, 0x3e000000, v43
	v_and_b32_e32 v41, 63, v120
	v_cvt_f32_u32_e32 v41, v41
	v_mul_f32_e32 v41, 0x3c800000, v41
	v_cos_f32_e32 v42, v41
	v_sin_f32_e32 v43, v41
	v_add_u32_e32 v120, v120, v122
	v_mul_f32_e32 v136, 0x3e000000, v42
	v_mul_f32_e32 v204, 0x3e000000, v43
	v_and_b32_e32 v41, 63, v121
	v_cvt_f32_u32_e32 v41, v41
	v_mul_f32_e32 v41, 0x3c800000, v41
	v_cos_f32_e32 v42, v41
	v_sin_f32_e32 v43, v41
	v_add_u32_e32 v121, v121, v123
	v_mul_f32_e32 v168, 0x3e000000, v42
	v_mul_f32_e32 v236, 0x3e000000, v43
	v_and_b32_e32 v41, 63, v120
	v_cvt_f32_u32_e32 v41, v41
	v_mul_f32_e32 v41, 0x3c800000, v41
	v_cos_f32_e32 v42, v41
	v_sin_f32_e32 v43, v41
	v_add_u32_e32 v120, v120, v122
	v_mul_f32_e32 v137, 0x3e000000, v42
	v_mul_f32_e32 v205, 0x3e000000, v43
	v_and_b32_e32 v41, 63, v121
	v_cvt_f32_u32_e32 v41, v41
	v_mul_f32_e32 v41, 0x3c800000, v41
	v_cos_f32_e32 v42, v41
	v_sin_f32_e32 v43, v41
	v_add_u32_e32 v121, v121, v123
	v_mul_f32_e32 v169, 0x3e000000, v42
	v_mul_f32_e32 v237, 0x3e000000, v43
	v_and_b32_e32 v41, 63, v120
	v_cvt_f32_u32_e32 v41, v41
	v_mul_f32_e32 v41, 0x3c800000, v41
	v_cos_f32_e32 v42, v41
	v_sin_f32_e32 v43, v41
	v_add_u32_e32 v120, v120, v122
	v_mul_f32_e32 v138, 0x3e000000, v42
	v_mul_f32_e32 v206, 0x3e000000, v43
	v_and_b32_e32 v41, 63, v121
	v_cvt_f32_u32_e32 v41, v41
	v_mul_f32_e32 v41, 0x3c800000, v41
	v_cos_f32_e32 v42, v41
	v_sin_f32_e32 v43, v41
	v_add_u32_e32 v121, v121, v123
	v_mul_f32_e32 v170, 0x3e000000, v42
	v_mul_f32_e32 v238, 0x3e000000, v43
	v_and_b32_e32 v41, 63, v120
	v_cvt_f32_u32_e32 v41, v41
	v_mul_f32_e32 v41, 0x3c800000, v41
	v_cos_f32_e32 v42, v41
	v_sin_f32_e32 v43, v41
	v_add_u32_e32 v120, v120, v122
	v_mul_f32_e32 v139, 0x3e000000, v42
	v_mul_f32_e32 v207, 0x3e000000, v43
	v_and_b32_e32 v41, 63, v121
	v_cvt_f32_u32_e32 v41, v41
	v_mul_f32_e32 v41, 0x3c800000, v41
	v_cos_f32_e32 v42, v41
	v_sin_f32_e32 v43, v41
	v_add_u32_e32 v121, v121, v123
	v_mul_f32_e32 v171, 0x3e000000, v42
	v_mul_f32_e32 v239, 0x3e000000, v43
	v_and_b32_e32 v41, 63, v120
	v_cvt_f32_u32_e32 v41, v41
	v_mul_f32_e32 v41, 0x3c800000, v41
	v_cos_f32_e32 v42, v41
	v_sin_f32_e32 v43, v41
	v_add_u32_e32 v120, v120, v122
	v_mul_f32_e32 v140, 0x3e000000, v42
	v_mul_f32_e32 v208, 0x3e000000, v43
	v_and_b32_e32 v41, 63, v121
	v_cvt_f32_u32_e32 v41, v41
	v_mul_f32_e32 v41, 0x3c800000, v41
	v_cos_f32_e32 v42, v41
	v_sin_f32_e32 v43, v41
	v_add_u32_e32 v121, v121, v123
; __device__ __forceinline__ void phase_prep(const Params& P, int l, unsigned char* lds) {
;     ...
;             for (int c = 0; c < 64; ++c) {
;                 float cv[4], sv[4];
; #pragma unroll
;                 for (int q = 0; q < 4; ++q) { const float rev = (float)((c * (cp0 + q)) & 63) * (1.0f / 64.0f); cv[q] = __builtin_amdgcn_cosf(rev) * 0.125f; sv[q] = __builtin_amdgcn_sinf(rev) * 0.125f; }
; #pragma unroll
;                 for (int t = 0; t < 8; ++t) { const float u = ub[t * 256 + c], u2 = ub2[t * 256 + c];
; #pragma unroll
;                     for (int q = 0; q < 4; ++q) { aC[q][t] += u * cv[q]; aS[q][t] += u2 * ((t == 0 && sp0) ? cv[q] : sv[q]); } }
	v_mul_f32_e32 v172, 0x3e000000, v42
	v_mul_f32_e32 v240, 0x3e000000, v43
	v_and_b32_e32 v41, 63, v120
	v_cvt_f32_u32_e32 v41, v41
	v_mul_f32_e32 v41, 0x3c800000, v41
	v_cos_f32_e32 v42, v41
	v_sin_f32_e32 v43, v41
	v_add_u32_e32 v120, v120, v122
	v_mul_f32_e32 v141, 0x3e000000, v42
	v_mul_f32_e32 v209, 0x3e000000, v43
	v_and_b32_e32 v41, 63, v121
	v_cvt_f32_u32_e32 v41, v41
	v_mul_f32_e32 v41, 0x3c800000, v41
	v_cos_f32_e32 v42, v41
	v_sin_f32_e32 v43, v41
	v_add_u32_e32 v121, v121, v123
	v_mul_f32_e32 v173, 0x3e000000, v42
	v_mul_f32_e32 v241, 0x3e000000, v43
	v_and_b32_e32 v41, 63, v120
	v_cvt_f32_u32_e32 v41, v41
	v_mul_f32_e32 v41, 0x3c800000, v41
	v_cos_f32_e32 v42, v41
	v_sin_f32_e32 v43, v41
	v_add_u32_e32 v120, v120, v122
	v_mul_f32_e32 v142, 0x3e000000, v42
	v_mul_f32_e32 v210, 0x3e000000, v43
	v_and_b32_e32 v41, 63, v121
	v_cvt_f32_u32_e32 v41, v41
	v_mul_f32_e32 v41, 0x3c800000, v41
	v_cos_f32_e32 v42, v41
	v_sin_f32_e32 v43, v41
	v_add_u32_e32 v121, v121, v123
	v_mul_f32_e32 v174, 0x3e000000, v42
	v_mul_f32_e32 v243, 0x3e000000, v43
	v_and_b32_e32 v41, 63, v120
	v_cvt_f32_u32_e32 v41, v41
	v_mul_f32_e32 v41, 0x3c800000, v41
	v_cos_f32_e32 v42, v41
	v_sin_f32_e32 v43, v41
	v_add_u32_e32 v120, v120, v122
	v_mul_f32_e32 v143, 0x3e000000, v42
	v_mul_f32_e32 v211, 0x3e000000, v43
	v_and_b32_e32 v41, 63, v121
	v_cvt_f32_u32_e32 v41, v41
	v_mul_f32_e32 v41, 0x3c800000, v41
	v_cos_f32_e32 v42, v41
	v_sin_f32_e32 v43, v41
	v_add_u32_e32 v121, v121, v123
	v_mul_f32_e32 v175, 0x3e000000, v42
	v_mul_f32_e32 v244, 0x3e000000, v43
	v_and_b32_e32 v41, 63, v120
	v_cvt_f32_u32_e32 v41, v41
	v_mul_f32_e32 v41, 0x3c800000, v41
	v_cos_f32_e32 v42, v41
	v_sin_f32_e32 v43, v41
	v_add_u32_e32 v120, v120, v122
	v_mul_f32_e32 v144, 0x3e000000, v42
	v_mul_f32_e32 v212, 0x3e000000, v43
	v_and_b32_e32 v41, 63, v121
	v_cvt_f32_u32_e32 v41, v41
	v_mul_f32_e32 v41, 0x3c800000, v41
	v_cos_f32_e32 v42, v41
	v_sin_f32_e32 v43, v41
	v_add_u32_e32 v121, v121, v123
	v_mul_f32_e32 v176, 0x3e000000, v42
	v_mul_f32_e32 v245, 0x3e000000, v43
	v_and_b32_e32 v41, 63, v120
	v_cvt_f32_u32_e32 v41, v41
	v_mul_f32_e32 v41, 0x3c800000, v41
	v_cos_f32_e32 v42, v41
	v_sin_f32_e32 v43, v41
	v_add_u32_e32 v120, v120, v122
	v_mul_f32_e32 v145, 0x3e000000, v42
	v_mul_f32_e32 v213, 0x3e000000, v43
	v_and_b32_e32 v41, 63, v121
	v_cvt_f32_u32_e32 v41, v41
	v_mul_f32_e32 v41, 0x3c800000, v41
	v_cos_f32_e32 v42, v41
	v_sin_f32_e32 v43, v41
	v_add_u32_e32 v121, v121, v123
	v_mul_f32_e32 v177, 0x3e000000, v42
	v_mul_f32_e32 v246, 0x3e000000, v43
	v_and_b32_e32 v41, 63, v120
	v_cvt_f32_u32_e32 v41, v41
	v_mul_f32_e32 v41, 0x3c800000, v41
	v_cos_f32_e32 v42, v41
	v_sin_f32_e32 v43, v41
	v_add_u32_e32 v120, v120, v122
	v_mul_f32_e32 v146, 0x3e000000, v42
	v_mul_f32_e32 v214, 0x3e000000, v43
	v_and_b32_e32 v41, 63, v121
	v_cvt_f32_u32_e32 v41, v41
	v_mul_f32_e32 v41, 0x3c800000, v41
	v_cos_f32_e32 v42, v41
	v_sin_f32_e32 v43, v41
	v_add_u32_e32 v121, v121, v123
	v_mul_f32_e32 v178, 0x3e000000, v42
	v_mul_f32_e32 v247, 0x3e000000, v43
	v_and_b32_e32 v41, 63, v120
	v_cvt_f32_u32_e32 v41, v41
	v_mul_f32_e32 v41, 0x3c800000, v41
	v_cos_f32_e32 v42, v41
	v_sin_f32_e32 v43, v41
	v_add_u32_e32 v120, v120, v122
	v_mul_f32_e32 v147, 0x3e000000, v42
	v_mul_f32_e32 v215, 0x3e000000, v43
	v_and_b32_e32 v41, 63, v121
	v_cvt_f32_u32_e32 v41, v41
	v_mul_f32_e32 v41, 0x3c800000, v41
	v_cos_f32_e32 v42, v41
	v_sin_f32_e32 v43, v41
	v_add_u32_e32 v121, v121, v123
	v_mul_f32_e32 v179, 0x3e000000, v42
	v_mul_f32_e32 v248, 0x3e000000, v43
	v_and_b32_e32 v41, 63, v120
	v_cvt_f32_u32_e32 v41, v41
	v_mul_f32_e32 v41, 0x3c800000, v41
	v_cos_f32_e32 v42, v41
	v_sin_f32_e32 v43, v41
	v_add_u32_e32 v120, v120, v122
	v_mul_f32_e32 v148, 0x3e000000, v42
	v_mul_f32_e32 v216, 0x3e000000, v43
	v_and_b32_e32 v41, 63, v121
	v_cvt_f32_u32_e32 v41, v41
	v_mul_f32_e32 v41, 0x3c800000, v41
	v_cos_f32_e32 v42, v41
	v_sin_f32_e32 v43, v41
	v_add_u32_e32 v121, v121, v123
	v_mul_f32_e32 v180, 0x3e000000, v42
	v_mul_f32_e32 v249, 0x3e000000, v43
	v_and_b32_e32 v41, 63, v120
	v_cvt_f32_u32_e32 v41, v41
	v_mul_f32_e32 v41, 0x3c800000, v41
	v_cos_f32_e32 v42, v41
	v_sin_f32_e32 v43, v41
	v_add_u32_e32 v120, v120, v122
	v_mul_f32_e32 v149, 0x3e000000, v42
	v_mul_f32_e32 v217, 0x3e000000, v43
	v_and_b32_e32 v41, 63, v121
	v_cvt_f32_u32_e32 v41, v41
	v_mul_f32_e32 v41, 0x3c800000, v41
	v_cos_f32_e32 v42, v41
	v_sin_f32_e32 v43, v41
	v_add_u32_e32 v121, v121, v123
	v_mul_f32_e32 v181, 0x3e000000, v42
	v_mul_f32_e32 v250, 0x3e000000, v43
	v_and_b32_e32 v41, 63, v120
	v_cvt_f32_u32_e32 v41, v41
	v_mul_f32_e32 v41, 0x3c800000, v41
	v_cos_f32_e32 v42, v41
	v_sin_f32_e32 v43, v41
	v_add_u32_e32 v120, v120, v122
	v_mul_f32_e32 v150, 0x3e000000, v42
	v_mul_f32_e32 v218, 0x3e000000, v43
	v_and_b32_e32 v41, 63, v121
	v_cvt_f32_u32_e32 v41, v41
	v_mul_f32_e32 v41, 0x3c800000, v41
	v_cos_f32_e32 v42, v41
	v_sin_f32_e32 v43, v41
	v_add_u32_e32 v121, v121, v123
	v_mul_f32_e32 v182, 0x3e000000, v42
	v_mul_f32_e32 v251, 0x3e000000, v43
	v_and_b32_e32 v41, 63, v120
	v_cvt_f32_u32_e32 v41, v41
	v_mul_f32_e32 v41, 0x3c800000, v41
	v_cos_f32_e32 v42, v41
	v_sin_f32_e32 v43, v41
	v_add_u32_e32 v120, v120, v122
	v_mul_f32_e32 v151, 0x3e000000, v42
	v_mul_f32_e32 v219, 0x3e000000, v43
	v_and_b32_e32 v41, 63, v121
	v_cvt_f32_u32_e32 v41, v41
	v_mul_f32_e32 v41, 0x3c800000, v41
	v_cos_f32_e32 v42, v41
	v_sin_f32_e32 v43, v41
	v_add_u32_e32 v121, v121, v123
	v_mul_f32_e32 v183, 0x3e000000, v42
	v_mul_f32_e32 v252, 0x3e000000, v43
	v_and_b32_e32 v41, 63, v120
	v_cvt_f32_u32_e32 v41, v41
	v_mul_f32_e32 v41, 0x3c800000, v41
	v_cos_f32_e32 v42, v41
	v_sin_f32_e32 v43, v41
; __device__ __forceinline__ void phase_prep(const Params& P, int l, unsigned char* lds) {
;     ...
;                 const int id = tid + 512 * rep, tok = id >> 5, ch = id & 31;
;                 const u32x4 w = *(const u32x4*)(proj + (size_t)(r0 + tok) * INW + PD_U + 8 * ch);
;                 f32x4 a0 = (f32x4){bflo(w.x), bfhi(w.x), bflo(w.y), bfhi(w.y)}, a1 = (f32x4){bflo(w.z), bfhi(w.z), bflo(w.w), bfhi(w.w)};
;                 float* d = U + tok * 256 + 8 * ch;
;                 if (!is_ctx) {
;                     const int tg = t0 - CTX + tok, mt = (tg == 0) ? SEQ / 2 : SEQ - tg;
;                     const u32x4 m = *(const u32x4*)(proj + ((size_t)b * TT + CTX + mt) * INW + PD_U + 8 * ch);
;                     const f32x4 m0 = (f32x4){bflo(m.x), bfhi(m.x), bflo(m.y), bfhi(m.y)}, m1 = (f32x4){bflo(m.z), bfhi(m.z), bflo(m.w), bfhi(m.w)};
;                     float* d2 = U2 + tok * 256 + 8 * ch;
;                     if (tg == 0) { *(f32x4*)d2 = m0; *(f32x4*)(d2 + 4) = m1; }
;                     else { *(f32x4*)d2 = a0 - m0; *(f32x4*)(d2 + 4) = a1 - m1; a0 = a0 + m0; a1 = a1 + m1; }
;                 }
;                 *(f32x4*)d = a0; *(f32x4*)(d + 4) = a1;
;     ...
;             for (int c = 0; c < 64; ++c) {
;                 float cv[4], sv[4];
; #pragma unroll
;                 for (int q = 0; q < 4; ++q) { const float rev = (float)((c * (cp0 + q)) & 63) * (1.0f / 64.0f); cv[q] = __builtin_amdgcn_cosf(rev) * 0.125f; sv[q] = __builtin_amdgcn_sinf(rev) * 0.125f; }
; #pragma unroll
;                 for (int t = 0; t < 8; ++t) { const float u = ub[t * 256 + c], u2 = ub2[t * 256 + c];
; #pragma unroll
;                     for (int q = 0; q < 4; ++q) { aC[q][t] += u * cv[q]; aS[q][t] += u2 * ((t == 0 && sp0) ? cv[q] : sv[q]); } }
	v_add_u32_e32 v120, v120, v122
	v_mul_f32_e32 v152, 0x3e000000, v42
	v_mul_f32_e32 v220, 0x3e000000, v43
	v_and_b32_e32 v41, 63, v121
	v_cvt_f32_u32_e32 v41, v41
	v_mul_f32_e32 v41, 0x3c800000, v41
	v_cos_f32_e32 v42, v41
	v_sin_f32_e32 v43, v41
	v_add_u32_e32 v121, v121, v123
	v_mul_f32_e32 v184, 0x3e000000, v42
	v_mul_f32_e32 v110, 0x3e000000, v43
	v_and_b32_e32 v41, 63, v120
	v_cvt_f32_u32_e32 v41, v41
	v_mul_f32_e32 v41, 0x3c800000, v41
	v_cos_f32_e32 v42, v41
	v_sin_f32_e32 v43, v41
	v_add_u32_e32 v120, v120, v122
	v_mul_f32_e32 v153, 0x3e000000, v42
	v_mul_f32_e32 v221, 0x3e000000, v43
	v_and_b32_e32 v41, 63, v121
	v_cvt_f32_u32_e32 v41, v41
	v_mul_f32_e32 v41, 0x3c800000, v41
	v_cos_f32_e32 v42, v41
	v_sin_f32_e32 v43, v41
	v_add_u32_e32 v121, v121, v123
	v_mul_f32_e32 v185, 0x3e000000, v42
	v_mul_f32_e32 v111, 0x3e000000, v43
	v_and_b32_e32 v41, 63, v120
	v_cvt_f32_u32_e32 v41, v41
	v_mul_f32_e32 v41, 0x3c800000, v41
	v_cos_f32_e32 v42, v41
	v_sin_f32_e32 v43, v41
	v_add_u32_e32 v120, v120, v122
	v_mul_f32_e32 v154, 0x3e000000, v42
	v_mul_f32_e32 v222, 0x3e000000, v43
	v_and_b32_e32 v41, 63, v121
	v_cvt_f32_u32_e32 v41, v41
	v_mul_f32_e32 v41, 0x3c800000, v41
	v_cos_f32_e32 v42, v41
	v_sin_f32_e32 v43, v41
	v_add_u32_e32 v121, v121, v123
	v_mul_f32_e32 v186, 0x3e000000, v42
	v_mul_f32_e32 v112, 0x3e000000, v43
	v_and_b32_e32 v41, 63, v120
	v_cvt_f32_u32_e32 v41, v41
	v_mul_f32_e32 v41, 0x3c800000, v41
	v_cos_f32_e32 v42, v41
	v_sin_f32_e32 v43, v41
	v_add_u32_e32 v120, v120, v122
	v_mul_f32_e32 v155, 0x3e000000, v42
	v_mul_f32_e32 v223, 0x3e000000, v43
	v_and_b32_e32 v41, 63, v121
	v_cvt_f32_u32_e32 v41, v41
	v_mul_f32_e32 v41, 0x3c800000, v41
	v_cos_f32_e32 v42, v41
	v_sin_f32_e32 v43, v41
	v_add_u32_e32 v121, v121, v123
	v_mul_f32_e32 v187, 0x3e000000, v42
	v_mul_f32_e32 v113, 0x3e000000, v43
	v_and_b32_e32 v41, 63, v120
	v_cvt_f32_u32_e32 v41, v41
	v_mul_f32_e32 v41, 0x3c800000, v41
	v_cos_f32_e32 v42, v41
	v_sin_f32_e32 v43, v41
	v_add_u32_e32 v120, v120, v122
	v_mul_f32_e32 v156, 0x3e000000, v42
	v_mul_f32_e32 v224, 0x3e000000, v43
	v_and_b32_e32 v41, 63, v121
	v_cvt_f32_u32_e32 v41, v41
	v_mul_f32_e32 v41, 0x3c800000, v41
	v_cos_f32_e32 v42, v41
	v_sin_f32_e32 v43, v41
	v_add_u32_e32 v121, v121, v123
	v_mul_f32_e32 v188, 0x3e000000, v42
	v_mul_f32_e32 v114, 0x3e000000, v43
	v_and_b32_e32 v41, 63, v120
	v_cvt_f32_u32_e32 v41, v41
	v_mul_f32_e32 v41, 0x3c800000, v41
	v_cos_f32_e32 v42, v41
	v_sin_f32_e32 v43, v41
	v_add_u32_e32 v120, v120, v122
	v_mul_f32_e32 v157, 0x3e000000, v42
	v_mul_f32_e32 v225, 0x3e000000, v43
	v_and_b32_e32 v41, 63, v121
	v_cvt_f32_u32_e32 v41, v41
	v_mul_f32_e32 v41, 0x3c800000, v41
	v_cos_f32_e32 v42, v41
	v_sin_f32_e32 v43, v41
	v_add_u32_e32 v121, v121, v123
	v_mul_f32_e32 v189, 0x3e000000, v42
	v_mul_f32_e32 v115, 0x3e000000, v43
	v_and_b32_e32 v41, 63, v120
	v_cvt_f32_u32_e32 v41, v41
	v_mul_f32_e32 v41, 0x3c800000, v41
	v_cos_f32_e32 v42, v41
	v_sin_f32_e32 v43, v41
	v_add_u32_e32 v120, v120, v122
	v_mul_f32_e32 v158, 0x3e000000, v42
	v_mul_f32_e32 v226, 0x3e000000, v43
	v_and_b32_e32 v41, 63, v121
	v_cvt_f32_u32_e32 v41, v41
	v_mul_f32_e32 v41, 0x3c800000, v41
	v_cos_f32_e32 v42, v41
	v_sin_f32_e32 v43, v41
	v_add_u32_e32 v121, v121, v123
	v_mul_f32_e32 v190, 0x3e000000, v42
	v_mul_f32_e32 v116, 0x3e000000, v43
	v_and_b32_e32 v41, 63, v120
	v_cvt_f32_u32_e32 v41, v41
	v_mul_f32_e32 v41, 0x3c800000, v41
	v_cos_f32_e32 v42, v41
	v_sin_f32_e32 v43, v41
	v_add_u32_e32 v120, v120, v122
	v_mul_f32_e32 v159, 0x3e000000, v42
	v_mul_f32_e32 v227, 0x3e000000, v43
	v_and_b32_e32 v41, 63, v121
	v_cvt_f32_u32_e32 v41, v41
	v_mul_f32_e32 v41, 0x3c800000, v41
	v_cos_f32_e32 v42, v41
	v_sin_f32_e32 v43, v41
	v_add_u32_e32 v121, v121, v123
	v_mul_f32_e32 v191, 0x3e000000, v42
	v_mul_f32_e32 v117, 0x3e000000, v43
	v_and_b32_e32 v41, 63, v120
	v_cvt_f32_u32_e32 v41, v41
	v_mul_f32_e32 v41, 0x3c800000, v41
	v_cos_f32_e32 v42, v41
	v_sin_f32_e32 v43, v41
	v_add_u32_e32 v120, v120, v122
	v_mul_f32_e32 v160, 0x3e000000, v42
	v_mul_f32_e32 v228, 0x3e000000, v43
	v_and_b32_e32 v41, 63, v121
	v_cvt_f32_u32_e32 v41, v41
	v_mul_f32_e32 v41, 0x3c800000, v41
	v_cos_f32_e32 v42, v41
	v_sin_f32_e32 v43, v41
	v_add_u32_e32 v121, v121, v123
	v_mul_f32_e32 v192, 0x3e000000, v42
	v_mul_f32_e32 v118, 0x3e000000, v43
	v_and_b32_e32 v41, 63, v120
	v_cvt_f32_u32_e32 v41, v41
	v_mul_f32_e32 v41, 0x3c800000, v41
	v_cos_f32_e32 v42, v41
	v_sin_f32_e32 v43, v41
	v_add_u32_e32 v120, v120, v122
	v_mul_f32_e32 v161, 0x3e000000, v42
	v_mul_f32_e32 v229, 0x3e000000, v43
	v_and_b32_e32 v41, 63, v121
	v_cvt_f32_u32_e32 v41, v41
	v_mul_f32_e32 v41, 0x3c800000, v41
	v_cos_f32_e32 v42, v41
	v_sin_f32_e32 v43, v41
	v_add_u32_e32 v121, v121, v123
	v_mul_f32_e32 v193, 0x3e000000, v42
	v_mul_f32_e32 v119, 0x3e000000, v43
	s_waitcnt vmcnt(0)
	v_lshlrev_b32_e32 v45, 16, v0
	v_and_b32_e32 v46, 0xffff0000, v0
	v_lshlrev_b32_e32 v47, 16, v1
	v_and_b32_e32 v48, 0xffff0000, v1
	v_lshlrev_b32_e32 v49, 16, v2
	v_and_b32_e32 v50, 0xffff0000, v2
	v_lshlrev_b32_e32 v51, 16, v3
	v_and_b32_e32 v52, 0xffff0000, v3
	v_lshlrev_b32_e32 v53, 16, v4
	v_and_b32_e32 v54, 0xffff0000, v4
	v_lshlrev_b32_e32 v55, 16, v5
	v_and_b32_e32 v56, 0xffff0000, v5
	v_lshlrev_b32_e32 v57, 16, v6
	v_and_b32_e32 v58, 0xffff0000, v6
	v_lshlrev_b32_e32 v59, 16, v7
	v_and_b32_e32 v60, 0xffff0000, v7
	v_lshlrev_b32_e32 v61, 16, v8
	v_and_b32_e32 v62, 0xffff0000, v8
	v_lshlrev_b32_e32 v63, 16, v9
	v_and_b32_e32 v64, 0xffff0000, v9
	v_lshlrev_b32_e32 v65, 16, v10
	v_and_b32_e32 v66, 0xffff0000, v10
	v_lshlrev_b32_e32 v67, 16, v11
	v_and_b32_e32 v68, 0xffff0000, v11
	v_lshlrev_b32_e32 v69, 16, v12
	v_and_b32_e32 v70, 0xffff0000, v12
	v_lshlrev_b32_e32 v71, 16, v13
	v_and_b32_e32 v72, 0xffff0000, v13
	v_lshlrev_b32_e32 v73, 16, v14
	v_and_b32_e32 v74, 0xffff0000, v14
	v_lshlrev_b32_e32 v75, 16, v15
	v_and_b32_e32 v76, 0xffff0000, v15
	s_and_b64 vcc, exec, s[42:43]
	s_cbranch_vccz .Ldft_wr_u
; __device__ __forceinline__ void phase_prep(const Params& P, int l, unsigned char* lds) {
;     ...
;                 const int id = tid + 512 * rep, tok = id >> 5, ch = id & 31;
;                 const u32x4 w = *(const u32x4*)(proj + (size_t)(r0 + tok) * INW + PD_U + 8 * ch);
;                 f32x4 a0 = (f32x4){bflo(w.x), bfhi(w.x), bflo(w.y), bfhi(w.y)}, a1 = (f32x4){bflo(w.z), bfhi(w.z), bflo(w.w), bfhi(w.w)};
;                 float* d = U + tok * 256 + 8 * ch;
;                 if (!is_ctx) {
;                     const int tg = t0 - CTX + tok, mt = (tg == 0) ? SEQ / 2 : SEQ - tg;
;                     const u32x4 m = *(const u32x4*)(proj + ((size_t)b * TT + CTX + mt) * INW + PD_U + 8 * ch);
;                     const f32x4 m0 = (f32x4){bflo(m.x), bfhi(m.x), bflo(m.y), bfhi(m.y)}, m1 = (f32x4){bflo(m.z), bfhi(m.z), bflo(m.w), bfhi(m.w)};
;                     float* d2 = U2 + tok * 256 + 8 * ch;
;                     if (tg == 0) { *(f32x4*)d2 = m0; *(f32x4*)(d2 + 4) = m1; }
;                     else { *(f32x4*)d2 = a0 - m0; *(f32x4*)(d2 + 4) = a1 - m1; a0 = a0 + m0; a1 = a1 + m1; }
;                 }
;                 *(f32x4*)d = a0; *(f32x4*)(d + 4) = a1;
	v_lshlrev_b32_e32 v77, 16, v16
	v_and_b32_e32 v78, 0xffff0000, v16
	v_lshlrev_b32_e32 v79, 16, v17
	v_and_b32_e32 v80, 0xffff0000, v17
	v_lshlrev_b32_e32 v81, 16, v18
	v_and_b32_e32 v82, 0xffff0000, v18
	v_lshlrev_b32_e32 v83, 16, v19
	v_and_b32_e32 v84, 0xffff0000, v19
	v_lshlrev_b32_e32 v85, 16, v20
	v_and_b32_e32 v86, 0xffff0000, v20
	v_lshlrev_b32_e32 v87, 16, v21
	v_and_b32_e32 v88, 0xffff0000, v21
	v_lshlrev_b32_e32 v89, 16, v22
	v_and_b32_e32 v90, 0xffff0000, v22
	v_lshlrev_b32_e32 v91, 16, v23
	v_and_b32_e32 v92, 0xffff0000, v23
	v_lshlrev_b32_e32 v93, 16, v24
	v_and_b32_e32 v94, 0xffff0000, v24
	v_lshlrev_b32_e32 v95, 16, v25
	v_and_b32_e32 v96, 0xffff0000, v25
	v_lshlrev_b32_e32 v97, 16, v26
	v_and_b32_e32 v98, 0xffff0000, v26
	v_lshlrev_b32_e32 v99, 16, v27
	v_and_b32_e32 v100, 0xffff0000, v27
	v_lshlrev_b32_e32 v101, 16, v28
	v_and_b32_e32 v102, 0xffff0000, v28
	v_lshlrev_b32_e32 v103, 16, v29
	v_and_b32_e32 v104, 0xffff0000, v29
	v_lshlrev_b32_e32 v105, 16, v30
	v_and_b32_e32 v106, 0xffff0000, v30
	v_lshlrev_b32_e32 v107, 16, v31
	v_and_b32_e32 v108, 0xffff0000, v31
	v_add_u32_e32 v42, s64, v32
	v_mov_b32_e32 v43, 0x100
	v_cmp_ne_u32_e64 s[50:51], v43, v42
	s_nop 1
	v_sub_f32_e32 v43, v45, v77
	v_add_f32_e32 v126, v45, v77
	v_cndmask_b32_e64 v77, v77, v43, s[50:51]
	v_cndmask_b32_e64 v45, v45, v126, s[50:51]
	v_sub_f32_e32 v43, v46, v78
	v_add_f32_e32 v126, v46, v78
	v_cndmask_b32_e64 v78, v78, v43, s[50:51]
	v_cndmask_b32_e64 v46, v46, v126, s[50:51]
	v_sub_f32_e32 v43, v47, v79
	v_add_f32_e32 v126, v47, v79
	v_cndmask_b32_e64 v79, v79, v43, s[50:51]
	v_cndmask_b32_e64 v47, v47, v126, s[50:51]
	v_sub_f32_e32 v43, v48, v80
	v_add_f32_e32 v126, v48, v80
	v_cndmask_b32_e64 v80, v80, v43, s[50:51]
	v_cndmask_b32_e64 v48, v48, v126, s[50:51]
	v_sub_f32_e32 v43, v49, v81
	v_add_f32_e32 v126, v49, v81
	v_cndmask_b32_e64 v81, v81, v43, s[50:51]
	v_cndmask_b32_e64 v49, v49, v126, s[50:51]
	v_sub_f32_e32 v43, v50, v82
	v_add_f32_e32 v126, v50, v82
	v_cndmask_b32_e64 v82, v82, v43, s[50:51]
	v_cndmask_b32_e64 v50, v50, v126, s[50:51]
	v_sub_f32_e32 v43, v51, v83
	v_add_f32_e32 v126, v51, v83
	v_cndmask_b32_e64 v83, v83, v43, s[50:51]
	v_cndmask_b32_e64 v51, v51, v126, s[50:51]
	v_sub_f32_e32 v43, v52, v84
	v_add_f32_e32 v126, v52, v84
	v_cndmask_b32_e64 v84, v84, v43, s[50:51]
	v_cndmask_b32_e64 v52, v52, v126, s[50:51]
	v_sub_f32_e32 v43, v53, v85
	v_add_f32_e32 v126, v53, v85
	v_cndmask_b32_e64 v85, v85, v43, s[50:51]
	v_cndmask_b32_e64 v53, v53, v126, s[50:51]
	v_sub_f32_e32 v43, v54, v86
	v_add_f32_e32 v126, v54, v86
	v_cndmask_b32_e64 v86, v86, v43, s[50:51]
	v_cndmask_b32_e64 v54, v54, v126, s[50:51]
	v_sub_f32_e32 v43, v55, v87
	v_add_f32_e32 v126, v55, v87
	v_cndmask_b32_e64 v87, v87, v43, s[50:51]
	v_cndmask_b32_e64 v55, v55, v126, s[50:51]
	v_sub_f32_e32 v43, v56, v88
	v_add_f32_e32 v126, v56, v88
	v_cndmask_b32_e64 v88, v88, v43, s[50:51]
	v_cndmask_b32_e64 v56, v56, v126, s[50:51]
	v_sub_f32_e32 v43, v57, v89
	v_add_f32_e32 v126, v57, v89
	v_cndmask_b32_e64 v89, v89, v43, s[50:51]
	v_cndmask_b32_e64 v57, v57, v126, s[50:51]
	v_sub_f32_e32 v43, v58, v90
	v_add_f32_e32 v126, v58, v90
	v_cndmask_b32_e64 v90, v90, v43, s[50:51]
	v_cndmask_b32_e64 v58, v58, v126, s[50:51]
	v_sub_f32_e32 v43, v59, v91
	v_add_f32_e32 v126, v59, v91
	v_cndmask_b32_e64 v91, v91, v43, s[50:51]
	v_cndmask_b32_e64 v59, v59, v126, s[50:51]
	v_sub_f32_e32 v43, v60, v92
	v_add_f32_e32 v126, v60, v92
	v_cndmask_b32_e64 v92, v92, v43, s[50:51]
	v_cndmask_b32_e64 v60, v60, v126, s[50:51]
	v_sub_f32_e32 v43, v61, v93
	v_add_f32_e32 v126, v61, v93
	v_cndmask_b32_e64 v93, v93, v43, s[50:51]
	v_cndmask_b32_e64 v61, v61, v126, s[50:51]
	v_sub_f32_e32 v43, v62, v94
	v_add_f32_e32 v126, v62, v94
	v_cndmask_b32_e64 v94, v94, v43, s[50:51]
	v_cndmask_b32_e64 v62, v62, v126, s[50:51]
	v_sub_f32_e32 v43, v63, v95
	v_add_f32_e32 v126, v63, v95
	v_cndmask_b32_e64 v95, v95, v43, s[50:51]
	v_cndmask_b32_e64 v63, v63, v126, s[50:51]
	v_sub_f32_e32 v43, v64, v96
	v_add_f32_e32 v126, v64, v96
	v_cndmask_b32_e64 v96, v96, v43, s[50:51]
	v_cndmask_b32_e64 v64, v64, v126, s[50:51]
	v_sub_f32_e32 v43, v65, v97
	v_add_f32_e32 v126, v65, v97
	v_cndmask_b32_e64 v97, v97, v43, s[50:51]
	v_cndmask_b32_e64 v65, v65, v126, s[50:51]
	v_sub_f32_e32 v43, v66, v98
	v_add_f32_e32 v126, v66, v98
	v_cndmask_b32_e64 v98, v98, v43, s[50:51]
	v_cndmask_b32_e64 v66, v66, v126, s[50:51]
	v_sub_f32_e32 v43, v67, v99
	v_add_f32_e32 v126, v67, v99
	v_cndmask_b32_e64 v99, v99, v43, s[50:51]
	v_cndmask_b32_e64 v67, v67, v126, s[50:51]
	v_sub_f32_e32 v43, v68, v100
	v_add_f32_e32 v126, v68, v100
	v_cndmask_b32_e64 v100, v100, v43, s[50:51]
	v_cndmask_b32_e64 v68, v68, v126, s[50:51]
	v_sub_f32_e32 v43, v69, v101
	v_add_f32_e32 v126, v69, v101
	v_cndmask_b32_e64 v101, v101, v43, s[50:51]
	v_cndmask_b32_e64 v69, v69, v126, s[50:51]
	v_sub_f32_e32 v43, v70, v102
	v_add_f32_e32 v126, v70, v102
	v_cndmask_b32_e64 v102, v102, v43, s[50:51]
	v_cndmask_b32_e64 v70, v70, v126, s[50:51]
	v_sub_f32_e32 v43, v71, v103
	v_add_f32_e32 v126, v71, v103
	v_cndmask_b32_e64 v103, v103, v43, s[50:51]
	v_cndmask_b32_e64 v71, v71, v126, s[50:51]
	v_sub_f32_e32 v43, v72, v104
	v_add_f32_e32 v126, v72, v104
	v_cndmask_b32_e64 v104, v104, v43, s[50:51]
	v_cndmask_b32_e64 v72, v72, v126, s[50:51]
	v_sub_f32_e32 v43, v73, v105
	v_add_f32_e32 v126, v73, v105
	v_cndmask_b32_e64 v105, v105, v43, s[50:51]
	v_cndmask_b32_e64 v73, v73, v126, s[50:51]
	v_sub_f32_e32 v43, v74, v106
	v_add_f32_e32 v126, v74, v106
	v_cndmask_b32_e64 v106, v106, v43, s[50:51]
	v_cndmask_b32_e64 v74, v74, v126, s[50:51]
	v_sub_f32_e32 v43, v75, v107
	v_add_f32_e32 v126, v75, v107
	v_cndmask_b32_e64 v107, v107, v43, s[50:51]
	v_cndmask_b32_e64 v75, v75, v126, s[50:51]
	v_sub_f32_e32 v43, v76, v108
	v_add_f32_e32 v126, v76, v108
	v_cndmask_b32_e64 v108, v108, v43, s[50:51]
	v_cndmask_b32_e64 v76, v76, v126, s[50:51]
	ds_write_b32 v36, v77
	ds_write_b32 v36, v78 offset:256
	ds_write_b32 v36, v79 offset:512
	ds_write_b32 v36, v80 offset:768
	ds_write_b32 v36, v81 offset:1024
	ds_write_b32 v36, v82 offset:1280
	ds_write_b32 v36, v83 offset:1536
	ds_write_b32 v36, v84 offset:1792
	ds_write_b32 v36, v85 offset:2048
	ds_write_b32 v36, v86 offset:2304
	ds_write_b32 v36, v87 offset:2560
	ds_write_b32 v36, v88 offset:2816
	ds_write_b32 v36, v89 offset:3072
	ds_write_b32 v36, v90 offset:3328
	ds_write_b32 v36, v91 offset:3584
	ds_write_b32 v36, v92 offset:3840
	ds_write_b32 v36, v93 offset:4096
	ds_write_b32 v36, v94 offset:4352
	ds_write_b32 v36, v95 offset:4608
	ds_write_b32 v36, v96 offset:4864
	ds_write_b32 v36, v97 offset:5120
	ds_write_b32 v36, v98 offset:5376
	ds_write_b32 v36, v99 offset:5632
	ds_write_b32 v36, v100 offset:5888
	ds_write_b32 v36, v101 offset:6144
	ds_write_b32 v36, v102 offset:6400
	ds_write_b32 v36, v103 offset:6656
	ds_write_b32 v36, v104 offset:6912
	ds_write_b32 v36, v105 offset:7168
	ds_write_b32 v36, v106 offset:7424
	ds_write_b32 v36, v107 offset:7680
	ds_write_b32 v36, v108 offset:7936
; __device__ __forceinline__ void phase_prep(const Params& P, int l, unsigned char* lds) {
;     ...
;                 *(f32x4*)d = a0; *(f32x4*)(d + 4) = a1;
;             }
;             __syncthreads();
;             const int n0 = (tid & 63) * 4, t8 = (tid >> 6) * 8, cp0 = n0 & 63, g = n0 >> 6;
;             const bool sp0 = (!is_ctx) && (t0 == CTX) && (t8 == 0);
;             float aC[4][8], aS[4][8];
; #pragma unroll
;             for (int q = 0; q < 4; ++q)
; #pragma unroll
;                 for (int t = 0; t < 8; ++t) { aC[q][t] = 0.f; aS[q][t] = 0.f; }
;             const float* ub = U + t8 * 256 + g * 64;
;             const float* ub2 = is_ctx ? ub : ub + 64 * 256;
.Ldft_wr_u:
	ds_write_b32 v35, v45
	ds_write_b32 v35, v46 offset:256
	ds_write_b32 v35, v47 offset:512
	ds_write_b32 v35, v48 offset:768
	ds_write_b32 v35, v49 offset:1024
	ds_write_b32 v35, v50 offset:1280
	ds_write_b32 v35, v51 offset:1536
	ds_write_b32 v35, v52 offset:1792
	ds_write_b32 v35, v53 offset:2048
	ds_write_b32 v35, v54 offset:2304
	ds_write_b32 v35, v55 offset:2560
	ds_write_b32 v35, v56 offset:2816
	ds_write_b32 v35, v57 offset:3072
	ds_write_b32 v35, v58 offset:3328
	ds_write_b32 v35, v59 offset:3584
	ds_write_b32 v35, v60 offset:3840
	ds_write_b32 v35, v61 offset:4096
	ds_write_b32 v35, v62 offset:4352
	ds_write_b32 v35, v63 offset:4608
	ds_write_b32 v35, v64 offset:4864
	ds_write_b32 v35, v65 offset:5120
	ds_write_b32 v35, v66 offset:5376
	ds_write_b32 v35, v67 offset:5632
	ds_write_b32 v35, v68 offset:5888
	ds_write_b32 v35, v69 offset:6144
	ds_write_b32 v35, v70 offset:6400
	ds_write_b32 v35, v71 offset:6656
	ds_write_b32 v35, v72 offset:6912
	ds_write_b32 v35, v73 offset:7168
	ds_write_b32 v35, v74 offset:7424
	ds_write_b32 v35, v75 offset:7680
	ds_write_b32 v35, v76 offset:7936
	s_waitcnt lgkmcnt(0)
	s_barrier
	s_lshl_b32 s7, s15, 14
	s_lshl_b32 s18, s13, 7
	s_add_u32 s7, s7, s18
	v_lshlrev_b32_e32 v35, 8, v33
	v_lshl_add_u32 v35, v34, 2, v35
	v_add_u32_e32 v35, s7, v35
	v_add_u32_e32 v36, 0x10000, v35
	s_and_b64 vcc, exec, s[42:43]
	s_cbranch_vccnz .Ldft_lat_a
	v_mov_b32_e32 v36, v35
